# grid barrier: non-leader workgroups poll the global generation word directly (one hop less per barrier)
# baseline (speedup 1.0000x reference)
; __device__ __forceinline__ unsigned xb_ld(unsigned* p)              { return __hip_atomic_load(p, __ATOMIC_RELAXED, __HIP_MEMORY_SCOPE_AGENT); }
; __device__ __forceinline__ unsigned xb_add(unsigned* p, unsigned v) { return __hip_atomic_fetch_add(p, v, __ATOMIC_RELAXED, __HIP_MEMORY_SCOPE_AGENT); }
; #define XB_SPIN(cond, bar) do { unsigned _sp = 0; while (cond) { __builtin_amdgcn_s_sleep(1); \
;     if ((++_sp & 255u) == 0u) { if (xb_ld(&(bar)[XB_TMO])) break; if (_sp > XB_SPIN_CAP) { atomicAdd(&(bar)[XB_TMO], 1u); break; } } } } while (0)
; __device__ __forceinline__ void xcd_barrier(const XcdBarrier& b) {
;     ...
;         const unsigned old = xb_add(&bar[XB_XSUB(b.x)], 1u);
;         const unsigned gen = old / nloc;
;         if (old + 1u == (gen + 1u) * nloc) {
;             __builtin_amdgcn_fence(__ATOMIC_RELEASE, "agent");
;             asm volatile("s_waitcnt vmcnt(0)" ::: "memory");
;             const unsigned og = xb_add(&bar[XB_TOP], 1u);
;             const unsigned tg = og / nx;
;             if (og + 1u == (tg + 1u) * nx) xb_add(&bar[XB_TOPGEN], 1u);
;             else XB_SPIN(xb_ld(&bar[XB_TOPGEN]) == tg, bar);
;             __builtin_amdgcn_fence(__ATOMIC_ACQUIRE, "agent");
;             xb_add(&bar[XB_XGEN(b.x)], 1u);
;             asm volatile("s_waitcnt vmcnt(0)" ::: "memory");
;         } else {
;             XB_SPIN(xb_ld(&bar[XB_XGEN(b.x)]) == gen, bar);
;             __builtin_amdgcn_fence(__ATOMIC_ACQUIRE, "agent");
;             asm volatile("s_waitcnt vmcnt(0)" ::: "memory");
;         }
.LBB0_145:
	v_readlane_b32 s2, v254, 21
	s_lshl_b32 s2, s2, 8
	v_readlane_b32 s6, v254, 19
	v_readlane_b32 s7, v254, 20
	s_add_u32 s6, s6, s2
	s_addc_u32 s7, s7, 0
	v_mov_b32_e32 v3, 0x1000
	v_mov_b32_e32 v5, 1
	v_sub_u32_e32 v6, 0, v4
	global_atomic_add v5, v3, v5, s[6:7] offset:1024 sc0
	v_cvt_f32_u32_e32 v3, v4
	v_rcp_iflag_f32_e32 v3, v3
	s_nop 0
	v_mul_f32_e32 v3, 0x4f7ffffe, v3
	v_cvt_u32_f32_e32 v3, v3
	v_mul_lo_u32 v6, v6, v3
	v_mul_hi_u32 v6, v3, v6
	v_add_u32_e32 v3, v3, v6
	s_waitcnt vmcnt(0)
	v_mul_hi_u32 v3, v5, v3
	v_mul_lo_u32 v6, v3, v4
	v_sub_u32_e32 v6, v5, v6
	v_add_u32_e32 v7, 1, v3
	v_cmp_ge_u32_e32 vcc, v6, v4
	v_add_u32_e32 v5, 1, v5
	s_nop 0
	v_cndmask_b32_e32 v3, v3, v7, vcc
	v_sub_u32_e32 v7, v6, v4
	v_cndmask_b32_e32 v6, v6, v7, vcc
	v_add_u32_e32 v7, 1, v3
	v_cmp_ge_u32_e32 vcc, v6, v4
	s_nop 1
	v_cndmask_b32_e32 v3, v3, v7, vcc
	v_mul_lo_u32 v6, v4, v3
	v_add_u32_e32 v4, v6, v4
	v_cmp_ne_u32_e32 vcc, v5, v4
	s_and_saveexec_b64 s[2:3], vcc
	s_xor_b64 s[14:15], exec, s[2:3]
	s_cbranch_execz .LBB0_159
	s_waitcnt lgkmcnt(0)
	v_readlane_b32 s8, v254, 19
	v_readlane_b32 s9, v254, 20
	v_mov_b32_e32 v2, 0
	s_add_u32 s8, s8, 0x3500
	s_addc_u32 s9, s9, 0
	global_load_dword v2, v2, s[8:9] sc1
	s_waitcnt vmcnt(0)
	v_cmp_eq_u32_e32 vcc, v2, v3
	s_and_saveexec_b64 s[16:17], vcc
	s_cbranch_execz .LBB0_158
	s_add_u32 s2, s68, 0x4200
	s_addc_u32 s3, s69, 0
	s_mov_b32 s26, 1
	s_mov_b64 s[10:11], 0
	v_mov_b32_e32 v2, 0
	s_branch .LBB0_149

; __device__ __forceinline__ unsigned xb_ld(unsigned* p)              { return __hip_atomic_load(p, __ATOMIC_RELAXED, __HIP_MEMORY_SCOPE_AGENT); }
; __device__ __forceinline__ unsigned xb_add(unsigned* p, unsigned v) { return __hip_atomic_fetch_add(p, v, __ATOMIC_RELAXED, __HIP_MEMORY_SCOPE_AGENT); }
; #define XB_SPIN(cond, bar) do { unsigned _sp = 0; while (cond) { __builtin_amdgcn_s_sleep(1); \
;     if ((++_sp & 255u) == 0u) { if (xb_ld(&(bar)[XB_TMO])) break; if (_sp > XB_SPIN_CAP) { atomicAdd(&(bar)[XB_TMO], 1u); break; } } } } while (0)
; __device__ __forceinline__ void xcd_barrier(const XcdBarrier& b) {
;     ...
;         const unsigned old = xb_add(&bar[XB_XSUB(b.x)], 1u);
;         const unsigned gen = old / nloc;
;         if (old + 1u == (gen + 1u) * nloc) {
;             __builtin_amdgcn_fence(__ATOMIC_RELEASE, "agent");
;             asm volatile("s_waitcnt vmcnt(0)" ::: "memory");
;             const unsigned og = xb_add(&bar[XB_TOP], 1u);
;             const unsigned tg = og / nx;
;             if (og + 1u == (tg + 1u) * nx) xb_add(&bar[XB_TOPGEN], 1u);
;             else XB_SPIN(xb_ld(&bar[XB_TOPGEN]) == tg, bar);
;             __builtin_amdgcn_fence(__ATOMIC_ACQUIRE, "agent");
;             xb_add(&bar[XB_XGEN(b.x)], 1u);
;             asm volatile("s_waitcnt vmcnt(0)" ::: "memory");
;         } else {
;             XB_SPIN(xb_ld(&bar[XB_XGEN(b.x)]) == gen, bar);
;             __builtin_amdgcn_fence(__ATOMIC_ACQUIRE, "agent");
;             asm volatile("s_waitcnt vmcnt(0)" ::: "memory");
;         }
.LBB0_357:
	v_readlane_b32 s2, v254, 21
	s_lshl_b32 s2, s2, 8
	v_readlane_b32 s6, v254, 19
	v_readlane_b32 s7, v254, 20
	s_add_u32 s6, s6, s2
	s_addc_u32 s7, s7, 0
	v_mov_b32_e32 v3, 0x1000
	v_mov_b32_e32 v5, 1
	v_sub_u32_e32 v6, 0, v4
	global_atomic_add v5, v3, v5, s[6:7] offset:1024 sc0
	v_cvt_f32_u32_e32 v3, v4
	v_rcp_iflag_f32_e32 v3, v3
	s_nop 0
	v_mul_f32_e32 v3, 0x4f7ffffe, v3
	v_cvt_u32_f32_e32 v3, v3
	v_mul_lo_u32 v6, v6, v3
	v_mul_hi_u32 v6, v3, v6
	v_add_u32_e32 v3, v3, v6
	s_waitcnt vmcnt(0)
	v_mul_hi_u32 v3, v5, v3
	v_mul_lo_u32 v6, v3, v4
	v_sub_u32_e32 v6, v5, v6
	v_add_u32_e32 v7, 1, v3
	v_cmp_ge_u32_e32 vcc, v6, v4
	v_add_u32_e32 v5, 1, v5
	s_nop 0
	v_cndmask_b32_e32 v3, v3, v7, vcc
	v_sub_u32_e32 v7, v6, v4
	v_cndmask_b32_e32 v6, v6, v7, vcc
	v_add_u32_e32 v7, 1, v3
	v_cmp_ge_u32_e32 vcc, v6, v4
	s_nop 1
	v_cndmask_b32_e32 v3, v3, v7, vcc
	v_mul_lo_u32 v6, v4, v3
	v_add_u32_e32 v4, v6, v4
	v_cmp_ne_u32_e32 vcc, v5, v4
	s_and_saveexec_b64 s[2:3], vcc
	s_xor_b64 s[8:9], exec, s[2:3]
	s_cbranch_execz .LBB0_371
	s_waitcnt lgkmcnt(0)
	v_readlane_b32 s12, v254, 19
	v_readlane_b32 s13, v254, 20
	v_mov_b32_e32 v2, 0
	s_add_u32 s12, s12, 0x3500
	s_addc_u32 s13, s13, 0
	global_load_dword v2, v2, s[12:13] sc1
	s_waitcnt vmcnt(0)
	v_cmp_eq_u32_e32 vcc, v2, v3
	s_and_saveexec_b64 s[10:11], vcc
	s_cbranch_execz .LBB0_370
	s_add_u32 s2, s68, 0x4200
	s_addc_u32 s3, s69, 0
	s_mov_b32 s26, 1
	s_mov_b64 s[16:17], 0
	v_mov_b32_e32 v2, 0
	s_branch .LBB0_361

; __device__ __forceinline__ unsigned xb_ld(unsigned* p)              { return __hip_atomic_load(p, __ATOMIC_RELAXED, __HIP_MEMORY_SCOPE_AGENT); }
; __device__ __forceinline__ unsigned xb_add(unsigned* p, unsigned v) { return __hip_atomic_fetch_add(p, v, __ATOMIC_RELAXED, __HIP_MEMORY_SCOPE_AGENT); }
; #define XB_SPIN(cond, bar) do { unsigned _sp = 0; while (cond) { __builtin_amdgcn_s_sleep(1); \
;     if ((++_sp & 255u) == 0u) { if (xb_ld(&(bar)[XB_TMO])) break; if (_sp > XB_SPIN_CAP) { atomicAdd(&(bar)[XB_TMO], 1u); break; } } } } while (0)
; __device__ __forceinline__ void xcd_barrier(const XcdBarrier& b) {
;     ...
;         const unsigned old = xb_add(&bar[XB_XSUB(b.x)], 1u);
;         const unsigned gen = old / nloc;
;         if (old + 1u == (gen + 1u) * nloc) {
;             __builtin_amdgcn_fence(__ATOMIC_RELEASE, "agent");
;             asm volatile("s_waitcnt vmcnt(0)" ::: "memory");
;             const unsigned og = xb_add(&bar[XB_TOP], 1u);
;             const unsigned tg = og / nx;
;             if (og + 1u == (tg + 1u) * nx) xb_add(&bar[XB_TOPGEN], 1u);
;             else XB_SPIN(xb_ld(&bar[XB_TOPGEN]) == tg, bar);
;             __builtin_amdgcn_fence(__ATOMIC_ACQUIRE, "agent");
;             xb_add(&bar[XB_XGEN(b.x)], 1u);
;             asm volatile("s_waitcnt vmcnt(0)" ::: "memory");
;         } else {
;             XB_SPIN(xb_ld(&bar[XB_XGEN(b.x)]) == gen, bar);
;             __builtin_amdgcn_fence(__ATOMIC_ACQUIRE, "agent");
;             asm volatile("s_waitcnt vmcnt(0)" ::: "memory");
;         }
.LBB0_596:
	v_readlane_b32 s2, v254, 21
	s_lshl_b32 s2, s2, 8
	v_readlane_b32 s6, v254, 19
	v_readlane_b32 s7, v254, 20
	s_add_u32 s6, s6, s2
	s_addc_u32 s7, s7, 0
	v_mov_b32_e32 v3, 0x1000
	v_mov_b32_e32 v5, 1
	v_sub_u32_e32 v6, 0, v4
	global_atomic_add v5, v3, v5, s[6:7] offset:1024 sc0
	v_cvt_f32_u32_e32 v3, v4
	v_rcp_iflag_f32_e32 v3, v3
	s_nop 0
	v_mul_f32_e32 v3, 0x4f7ffffe, v3
	v_cvt_u32_f32_e32 v3, v3
	v_mul_lo_u32 v6, v6, v3
	v_mul_hi_u32 v6, v3, v6
	v_add_u32_e32 v3, v3, v6
	s_waitcnt vmcnt(0)
	v_mul_hi_u32 v3, v5, v3
	v_mul_lo_u32 v6, v3, v4
	v_sub_u32_e32 v6, v5, v6
	v_add_u32_e32 v7, 1, v3
	v_cmp_ge_u32_e32 vcc, v6, v4
	v_add_u32_e32 v5, 1, v5
	s_nop 0
	v_cndmask_b32_e32 v3, v3, v7, vcc
	v_sub_u32_e32 v7, v6, v4
	v_cndmask_b32_e32 v6, v6, v7, vcc
	v_add_u32_e32 v7, 1, v3
	v_cmp_ge_u32_e32 vcc, v6, v4
	s_nop 1
	v_cndmask_b32_e32 v3, v3, v7, vcc
	v_mul_lo_u32 v6, v4, v3
	v_add_u32_e32 v4, v6, v4
	v_cmp_ne_u32_e32 vcc, v5, v4
	s_and_saveexec_b64 s[2:3], vcc
	s_xor_b64 s[8:9], exec, s[2:3]
	s_cbranch_execz .LBB0_610
	s_waitcnt lgkmcnt(0)
	v_readlane_b32 s12, v254, 19
	v_readlane_b32 s13, v254, 20
	v_mov_b32_e32 v2, 0
	s_add_u32 s12, s12, 0x3500
	s_addc_u32 s13, s13, 0
	global_load_dword v2, v2, s[12:13] sc1
	s_waitcnt vmcnt(0)
	v_cmp_eq_u32_e32 vcc, v2, v3
	s_and_saveexec_b64 s[10:11], vcc
	s_cbranch_execz .LBB0_609
	s_add_u32 s2, s68, 0x4200
	s_addc_u32 s3, s69, 0
	s_mov_b32 s24, 1
	s_mov_b64 s[14:15], 0
	v_mov_b32_e32 v2, 0
	s_branch .LBB0_600

; __device__ __forceinline__ unsigned xb_ld(unsigned* p)              { return __hip_atomic_load(p, __ATOMIC_RELAXED, __HIP_MEMORY_SCOPE_AGENT); }
; __device__ __forceinline__ unsigned xb_add(unsigned* p, unsigned v) { return __hip_atomic_fetch_add(p, v, __ATOMIC_RELAXED, __HIP_MEMORY_SCOPE_AGENT); }
; #define XB_SPIN(cond, bar) do { unsigned _sp = 0; while (cond) { __builtin_amdgcn_s_sleep(1); \
;     if ((++_sp & 255u) == 0u) { if (xb_ld(&(bar)[XB_TMO])) break; if (_sp > XB_SPIN_CAP) { atomicAdd(&(bar)[XB_TMO], 1u); break; } } } } while (0)
; __device__ __forceinline__ void xcd_barrier(const XcdBarrier& b) {
;     ...
;         const unsigned old = xb_add(&bar[XB_XSUB(b.x)], 1u);
;         const unsigned gen = old / nloc;
;         if (old + 1u == (gen + 1u) * nloc) {
;             __builtin_amdgcn_fence(__ATOMIC_RELEASE, "agent");
;             asm volatile("s_waitcnt vmcnt(0)" ::: "memory");
;             const unsigned og = xb_add(&bar[XB_TOP], 1u);
;             const unsigned tg = og / nx;
;             if (og + 1u == (tg + 1u) * nx) xb_add(&bar[XB_TOPGEN], 1u);
;             else XB_SPIN(xb_ld(&bar[XB_TOPGEN]) == tg, bar);
;             __builtin_amdgcn_fence(__ATOMIC_ACQUIRE, "agent");
;             xb_add(&bar[XB_XGEN(b.x)], 1u);
;             asm volatile("s_waitcnt vmcnt(0)" ::: "memory");
;         } else {
;             XB_SPIN(xb_ld(&bar[XB_XGEN(b.x)]) == gen, bar);
;             __builtin_amdgcn_fence(__ATOMIC_ACQUIRE, "agent");
;             asm volatile("s_waitcnt vmcnt(0)" ::: "memory");
;         }
.LBB0_818:
	v_readlane_b32 s2, v254, 21
	s_lshl_b32 s2, s2, 8
	v_readlane_b32 s6, v254, 19
	v_readlane_b32 s7, v254, 20
	s_add_u32 s6, s6, s2
	s_addc_u32 s7, s7, 0
	v_mov_b32_e32 v3, 0x1000
	v_mov_b32_e32 v5, 1
	v_sub_u32_e32 v6, 0, v4
	global_atomic_add v5, v3, v5, s[6:7] offset:1024 sc0
	v_cvt_f32_u32_e32 v3, v4
	v_rcp_iflag_f32_e32 v3, v3
	s_nop 0
	v_mul_f32_e32 v3, 0x4f7ffffe, v3
	v_cvt_u32_f32_e32 v3, v3
	v_mul_lo_u32 v6, v6, v3
	v_mul_hi_u32 v6, v3, v6
	v_add_u32_e32 v3, v3, v6
	s_waitcnt vmcnt(0)
	v_mul_hi_u32 v3, v5, v3
	v_mul_lo_u32 v6, v3, v4
	v_sub_u32_e32 v6, v5, v6
	v_add_u32_e32 v7, 1, v3
	v_cmp_ge_u32_e32 vcc, v6, v4
	v_add_u32_e32 v5, 1, v5
	s_nop 0
	v_cndmask_b32_e32 v3, v3, v7, vcc
	v_sub_u32_e32 v7, v6, v4
	v_cndmask_b32_e32 v6, v6, v7, vcc
	v_add_u32_e32 v7, 1, v3
	v_cmp_ge_u32_e32 vcc, v6, v4
	s_nop 1
	v_cndmask_b32_e32 v3, v3, v7, vcc
	v_mul_lo_u32 v6, v4, v3
	v_add_u32_e32 v4, v6, v4
	v_cmp_ne_u32_e32 vcc, v5, v4
	s_and_saveexec_b64 s[2:3], vcc
	s_xor_b64 s[8:9], exec, s[2:3]
	s_cbranch_execz .LBB0_832
	s_waitcnt lgkmcnt(0)
	v_readlane_b32 s12, v254, 19
	v_readlane_b32 s13, v254, 20
	v_mov_b32_e32 v2, 0
	s_add_u32 s12, s12, 0x3500
	s_addc_u32 s13, s13, 0
	global_load_dword v2, v2, s[12:13] sc1
	s_waitcnt vmcnt(0)
	v_cmp_eq_u32_e32 vcc, v2, v3
	s_and_saveexec_b64 s[10:11], vcc
	s_cbranch_execz .LBB0_831
	s_add_u32 s2, s68, 0x4200
	s_addc_u32 s3, s69, 0
	s_mov_b32 s28, 1
	s_mov_b64 s[14:15], 0
	v_mov_b32_e32 v2, 0
	s_branch .LBB0_822

; __device__ __forceinline__ unsigned xb_ld(unsigned* p)              { return __hip_atomic_load(p, __ATOMIC_RELAXED, __HIP_MEMORY_SCOPE_AGENT); }
; __device__ __forceinline__ unsigned xb_add(unsigned* p, unsigned v) { return __hip_atomic_fetch_add(p, v, __ATOMIC_RELAXED, __HIP_MEMORY_SCOPE_AGENT); }
; #define XB_SPIN(cond, bar) do { unsigned _sp = 0; while (cond) { __builtin_amdgcn_s_sleep(1); \
;     if ((++_sp & 255u) == 0u) { if (xb_ld(&(bar)[XB_TMO])) break; if (_sp > XB_SPIN_CAP) { atomicAdd(&(bar)[XB_TMO], 1u); break; } } } } while (0)
; __device__ __forceinline__ void xcd_barrier(const XcdBarrier& b) {
;     ...
;         const unsigned old = xb_add(&bar[XB_XSUB(b.x)], 1u);
;         const unsigned gen = old / nloc;
;         if (old + 1u == (gen + 1u) * nloc) {
;             __builtin_amdgcn_fence(__ATOMIC_RELEASE, "agent");
;             asm volatile("s_waitcnt vmcnt(0)" ::: "memory");
;             const unsigned og = xb_add(&bar[XB_TOP], 1u);
;             const unsigned tg = og / nx;
;             if (og + 1u == (tg + 1u) * nx) xb_add(&bar[XB_TOPGEN], 1u);
;             else XB_SPIN(xb_ld(&bar[XB_TOPGEN]) == tg, bar);
;             __builtin_amdgcn_fence(__ATOMIC_ACQUIRE, "agent");
;             xb_add(&bar[XB_XGEN(b.x)], 1u);
;             asm volatile("s_waitcnt vmcnt(0)" ::: "memory");
;         } else {
;             XB_SPIN(xb_ld(&bar[XB_XGEN(b.x)]) == gen, bar);
;             __builtin_amdgcn_fence(__ATOMIC_ACQUIRE, "agent");
;             asm volatile("s_waitcnt vmcnt(0)" ::: "memory");
;         }
.LBB0_1103:
	v_readlane_b32 s2, v254, 21
	s_lshl_b32 s2, s2, 8
	v_readlane_b32 s6, v254, 19
	v_readlane_b32 s7, v254, 20
	s_add_u32 s6, s6, s2
	s_addc_u32 s7, s7, 0
	v_mov_b32_e32 v3, 0x1000
	v_mov_b32_e32 v5, 1
	v_sub_u32_e32 v6, 0, v4
	global_atomic_add v5, v3, v5, s[6:7] offset:1024 sc0
	v_cvt_f32_u32_e32 v3, v4
	v_rcp_iflag_f32_e32 v3, v3
	s_nop 0
	v_mul_f32_e32 v3, 0x4f7ffffe, v3
	v_cvt_u32_f32_e32 v3, v3
	v_mul_lo_u32 v6, v6, v3
	v_mul_hi_u32 v6, v3, v6
	v_add_u32_e32 v3, v3, v6
	s_waitcnt vmcnt(0)
	v_mul_hi_u32 v3, v5, v3
	v_mul_lo_u32 v6, v3, v4
	v_sub_u32_e32 v6, v5, v6
	v_add_u32_e32 v7, 1, v3
	v_cmp_ge_u32_e32 vcc, v6, v4
	v_add_u32_e32 v5, 1, v5
	s_nop 0
	v_cndmask_b32_e32 v3, v3, v7, vcc
	v_sub_u32_e32 v7, v6, v4
	v_cndmask_b32_e32 v6, v6, v7, vcc
	v_add_u32_e32 v7, 1, v3
	v_cmp_ge_u32_e32 vcc, v6, v4
	s_nop 1
	v_cndmask_b32_e32 v3, v3, v7, vcc
	v_mul_lo_u32 v6, v4, v3
	v_add_u32_e32 v4, v6, v4
	v_cmp_ne_u32_e32 vcc, v5, v4
	s_and_saveexec_b64 s[2:3], vcc
	s_xor_b64 s[8:9], exec, s[2:3]
	s_cbranch_execz .LBB0_1117
	s_waitcnt lgkmcnt(0)
	v_readlane_b32 s12, v254, 19
	v_readlane_b32 s13, v254, 20
	v_mov_b32_e32 v2, 0
	s_add_u32 s12, s12, 0x3500
	s_addc_u32 s13, s13, 0
	global_load_dword v2, v2, s[12:13] sc1
	s_waitcnt vmcnt(0)
	v_cmp_eq_u32_e32 vcc, v2, v3
	s_and_saveexec_b64 s[10:11], vcc
	s_cbranch_execz .LBB0_1116
	s_add_u32 s2, s68, 0x4200
	s_addc_u32 s3, s69, 0
	s_mov_b32 s28, 1
	s_mov_b64 s[18:19], 0
	v_mov_b32_e32 v2, 0
	s_branch .LBB0_1107
